# baseline (speedup 1.0000x reference)
; #define MFMA(a, b, c) __builtin_amdgcn_mfma_f32_32x32x16_bf16((a), (b), (c), 0, 0, 0)
; DI void qk_acc(f32x16 (&st)[2], const bf16x8 (&qf)[4], const char* sb, const int (&foff)[4]) {
; #pragma unroll
;   for (int kb = 0; kb < 2; ++kb)
; #pragma unroll
;     for (int ks = 0; ks < 4; ++ks) {
;       const bf16x8 kf = *(const bf16x8*)(sb + kb * 4096 + foff[ks]);
;       st[kb] = MFMA(kf, qf[ks], st[kb]);
;     }
; }
; template <int DV, bool SEL, bool TERM> ...
;     ...
;     const float dbase = (float)(tqp - kp_mul * (k0 + 4 * h));
;     f32x16 st[2];
;     if (relevant) {
;       const float tb = -slope2 * dbase - mref;
; #pragma unroll
;       for (int kb = 0; kb < 2; ++kb)
; #pragma unroll
;         for (int i = 0; i < 16; ++i) st[kb][i] = __builtin_fmaf(sk, (float)(kb * 32 + (i & 3) + 8 * (i >> 2)), tb);
;       qk_acc(st, qf, sb, foff);
.LBB0_2003:
	s_lshl_b32 s1, s86, 6
	v_or_b32_e32 v0, s1, v166
	v_sub_u32_e32 v2, v130, v0
	s_or_b32 s4, s1, 63
	v_cvt_f32_i32_e32 v0, v2
	s_mul_hi_u32 s0, s97, 0xaaaaaaab
	s_waitcnt lgkmcnt(0)
	v_subrev_u32_e32 v3, s1, v152
	v_subrev_u32_e32 v4, s4, v151
	s_lshr_b32 s0, s0, 1
	v_cmp_lt_i32_e32 vcc, -1, v3
	v_cmp_gt_i32_e64 s[4:5], s90, v4
	s_mul_i32 s0, s0, 0xfffee000
	s_and_b64 s[4:5], vcc, s[4:5]
	s_barrier
	s_and_saveexec_b64 s[8:9], s[4:5]
	s_cbranch_execz .LBB0_2005
	s_add_i32 s1, s95, s0
	v_add_u32_e32 v5, s1, v173
	ds_read_b128 v[6:9], v5
	v_fma_f32 v10, -v132, v0, -v131
	v_fma_f32 v80, 0, v132, v10
	v_add_f32_e32 v81, v132, v10
	v_pk_fma_f32 v[82:83], v[140:141], s[22:23], v[10:11] op_sel_hi:[1,1,0]
	v_pk_fma_f32 v[84:85], v[140:141], s[24:25], v[10:11] op_sel_hi:[1,1,0]
	v_pk_fma_f32 v[86:87], v[140:141], s[26:27], v[10:11] op_sel_hi:[1,1,0]
	v_pk_fma_f32 v[88:89], v[140:141], s[28:29], v[10:11] op_sel_hi:[1,1,0]
	v_pk_fma_f32 v[90:91], v[140:141], s[30:31], v[10:11] op_sel_hi:[1,1,0]
	v_pk_fma_f32 v[92:93], v[140:141], s[34:35], v[10:11] op_sel_hi:[1,1,0]
	v_pk_fma_f32 v[94:95], v[140:141], s[36:37], v[10:11] op_sel_hi:[1,1,0]
	v_add_u32_e32 v11, s1, v175
	v_add_u32_e32 v12, s1, v176
	v_add_u32_e32 v13, s1, v174
	ds_read_b128 v[224:227], v11
	ds_read_b128 v[228:231], v12
	ds_read_b128 v[232:235], v13
	ds_read_b128 v[236:239], v5 offset:4096
	ds_read_b128 v[240:243], v11 offset:4096
	ds_read_b128 v[244:247], v12 offset:4096
	ds_read_b128 v[248:251], v13 offset:4096
	s_waitcnt lgkmcnt(7)
	v_mfma_f32_32x32x16_bf16 v[80:95], v[6:9], v[112:115], v[80:95]
	v_mov_b32_e32 v133, v132
	v_fma_f32 v110, v132, s38, v10
	v_fma_f32 v111, v133, s39, v10
	v_pk_fma_f32 v[108:109], v[132:133], s[40:41], v[10:11] op_sel_hi:[1,1,0]
	v_pk_fma_f32 v[106:107], v[132:133], s[42:43], v[10:11] op_sel_hi:[1,1,0]
	v_pk_fma_f32 v[104:105], v[132:133], s[44:45], v[10:11] op_sel_hi:[1,1,0]
	s_waitcnt lgkmcnt(6)
	v_mfma_f32_32x32x16_bf16 v[80:95], v[224:227], v[116:119], v[80:95]
	v_fma_f32 v102, v132, s46, v10
	v_fma_f32 v103, v133, s47, v10
	v_fma_f32 v100, v132, s48, v10
	v_fma_f32 v101, v133, s49, v10
	v_pk_fma_f32 v[98:99], v[132:133], s[50:51], v[10:11] op_sel_hi:[1,1,0]
	v_pk_fma_f32 v[96:97], v[142:143], s[52:53], v[10:11] op_sel_hi:[1,1,0]
	s_waitcnt lgkmcnt(5)
	v_mfma_f32_32x32x16_bf16 v[80:95], v[228:231], v[120:123], v[80:95]
	s_waitcnt lgkmcnt(4)
	v_mfma_f32_32x32x16_bf16 v[80:95], v[232:235], v[124:127], v[80:95]
	s_waitcnt lgkmcnt(3)
	v_mfma_f32_32x32x16_bf16 v[96:111], v[236:239], v[112:115], v[96:111]
	s_waitcnt lgkmcnt(2)
	v_mfma_f32_32x32x16_bf16 v[96:111], v[240:243], v[116:119], v[96:111]
	s_waitcnt lgkmcnt(1)
	v_mfma_f32_32x32x16_bf16 v[96:111], v[244:247], v[120:123], v[96:111]
	s_waitcnt lgkmcnt(0)
	v_mfma_f32_32x32x16_bf16 v[96:111], v[248:251], v[124:127], v[96:111]

; DI unsigned pack2(float a, float b) { v2f f = {a, b}; return __builtin_bit_cast(unsigned, __builtin_convertvector(f, v2bf)); }
; DI float bflo(unsigned v) { return __uint_as_float(v << 16); }
; DI float bfhi(unsigned v) { return __uint_as_float(v & 0xffff0000u); }
; DI float fexp2(float x) { return __builtin_amdgcn_exp2f(x); }
; DI float xsumh(float v) { const u32x2 r = __builtin_amdgcn_permlane32_swap(__float_as_uint(v), __float_as_uint(v), false, false); return __uint_as_float(r[0]) + __uint_as_float(r[1]); }
; DI void dil_attn_phase(const Params& p, char* smem) {
;     ...
;     l = xsumh(l);
;     const float lse_j = m + __builtin_amdgcn_logf(l);
;     const float lse_1 = p.partlse[tok * 8 + hg * 2 + half];
;     const float M = fmaxf(lse_j, lse_1);
;     const float wj = fexp2(lse_j - M), w1 = fexp2(lse_1 - M);
;     const float inv = 1.f / (wj + w1);
;     const float cj = wj * inv / l, c1 = w1 * inv;
; #pragma unroll
;     for (int dc = 0; dc < 4; ++dc)
; #pragma unroll
;       for (int g4 = 0; g4 < 4; ++g4) {
;         const int col = hg * 256 + half * 128 + 32 * dc + 8 * g4 + 4 * h;
;         const u32x2 zz = *(const u32x2*)(p.qkvz + tok * LD + 2560 + col);
;         const u32x2 pp = *(const u32x2*)(p.part + tok * 1024 + col);
;         u32x2 o;
;         o.x = pack2((ot[dc][4 * g4] * cj + bflo(pp.x) * c1) * bflo(zz.x), (ot[dc][4 * g4 + 1] * cj + bfhi(pp.x) * c1) * bfhi(zz.x));
;         o.y = pack2((ot[dc][4 * g4 + 2] * cj + bflo(pp.y) * c1) * bflo(zz.y), (ot[dc][4 * g4 + 3] * cj + bfhi(pp.y) * c1) * bfhi(zz.y));
;         *(u32x2*)(p.u + tok * 1024 + col) = o;
.LBB0_2075:
	v_mov_b32_e32 v0, v155
	s_nop 1
	v_permlane32_swap_b32_e32 v155, v0
	v_readlane_b32 s0, v255, 0
	s_waitcnt vmcnt(0)
	v_add_f32_e32 v0, v155, v0
	v_readlane_b32 s1, v255, 1
	s_waitcnt vmcnt(0)
	v_log_f32_e32 v2, v0
	s_load_dwordx2 s[0:1], s[0:1], 0x118
	s_mov_b32 s91, s11
	s_lshl_b32 s10, s13, 2
	v_add_f32_e32 v4, v156, v2
	v_lshlrev_b64 v[2:3], 5, v[128:129]
	s_waitcnt lgkmcnt(0)
	v_lshl_add_u64 v[2:3], s[0:1], 0, v[2:3]
	v_lshl_add_u64 v[2:3], v[2:3], 0, s[90:91]
	v_lshl_add_u64 v[2:3], v[2:3], 0, s[10:11]
	global_load_dword v2, v[2:3], off
	v_readlane_b32 s4, v255, 18
	v_lshlrev_b64 v[12:13], 11, v[128:129]
	v_readlane_b32 s6, v255, 20
	v_readlane_b32 s7, v255, 21
	v_readlane_b32 s5, v255, 19
	s_waitcnt vmcnt(0)
	v_max_f32_e32 v3, v2, v2
	v_max_f32_e32 v3, v4, v3
	v_sub_f32_e32 v4, v4, v3
	v_sub_f32_e32 v2, v2, v3
	v_exp_f32_e32 v4, v4
	v_exp_f32_e32 v3, v2
	s_nop 0
	v_add_f32_e32 v2, v4, v3
	v_div_scale_f32 v5, s[0:1], v2, v2, 1.0
	v_rcp_f32_e32 v6, v5
	s_nop 0
	v_fma_f32 v7, -v5, v6, 1.0
	v_fmac_f32_e32 v6, v7, v6
	v_div_scale_f32 v7, vcc, 1.0, v2, 1.0
	v_mul_f32_e32 v8, v7, v6
	v_fma_f32 v9, -v5, v8, v7
	v_fmac_f32_e32 v8, v9, v6
	v_fma_f32 v5, -v5, v8, v7
	v_div_fmas_f32 v5, v5, v6, v8
	v_div_fixup_f32 v5, v5, v2, 1.0
	v_mul_f32_e32 v2, v4, v5
	v_div_scale_f32 v4, s[0:1], v0, v0, v2
	v_rcp_f32_e32 v6, v4
	s_mov_b64 s[0:1], 0x1400
	v_lshl_add_u64 v[10:11], v[130:131], 0, s[0:1]
	s_mov_b64 s[0:1], 0
	v_fma_f32 v7, -v4, v6, 1.0
	v_fmac_f32_e32 v6, v7, v6
	v_div_scale_f32 v7, vcc, v2, v0, v2
	v_mul_f32_e32 v8, v7, v6
	v_fma_f32 v9, -v4, v8, v7
	v_fmac_f32_e32 v8, v9, v6
	v_fma_f32 v4, -v4, v8, v7
	v_div_fmas_f32 v4, v4, v6, v8
	v_div_fixup_f32 v2, v4, v0, v2
	v_lshl_or_b32 v0, v154, 2, s15
	v_or_b32_e32 v0, s14, v0
	v_lshlrev_b32_e32 v0, 1, v0
	v_lshl_add_u64 v[8:9], s[6:7], 0, v[12:13]
	v_lshl_add_u64 v[8:9], v[8:9], 0, v[0:1]
	v_lshl_add_u64 v[6:7], v[10:11], 0, v[0:1]
	global_load_dwordx2 v[206:207], v[6:7], off offset:16
	global_load_dwordx2 v[208:209], v[8:9], off offset:16
	global_load_dwordx2 v[210:211], v[6:7], off offset:32
	global_load_dwordx2 v[212:213], v[8:9], off offset:32
	global_load_dwordx2 v[214:215], v[6:7], off offset:48
	global_load_dwordx2 v[216:217], v[8:9], off offset:48
	global_load_dwordx2 v[218:219], v[6:7], off offset:64
	global_load_dwordx2 v[220:221], v[8:9], off offset:64
	global_load_dwordx2 v[224:225], v[6:7], off offset:80
	global_load_dwordx2 v[226:227], v[8:9], off offset:80
	global_load_dwordx2 v[228:229], v[6:7], off offset:96
	global_load_dwordx2 v[230:231], v[8:9], off offset:96
	global_load_dwordx2 v[232:233], v[6:7], off offset:112
	global_load_dwordx2 v[234:235], v[8:9], off offset:112
	global_load_dwordx2 v[236:237], v[6:7], off offset:128
	global_load_dwordx2 v[238:239], v[8:9], off offset:128
	global_load_dwordx2 v[240:241], v[6:7], off offset:144
	global_load_dwordx2 v[242:243], v[8:9], off offset:144
	global_load_dwordx2 v[244:245], v[6:7], off offset:160
	global_load_dwordx2 v[246:247], v[8:9], off offset:160
	global_load_dwordx2 v[248:249], v[6:7], off offset:176
	global_load_dwordx2 v[250:251], v[8:9], off offset:176
	global_load_dwordx2 v[14:15], v[8:9], off
	v_mul_f32_e32 v4, v3, v5
	global_load_dwordx2 v[6:7], v[6:7], off
	v_pk_mul_f32 v[64:65], v[64:65], v[2:3] op_sel_hi:[1,0]
	v_readlane_b32 s4, v255, 14
	v_readlane_b32 s5, v255, 15
	v_readlane_b32 s6, v255, 16
	v_readlane_b32 s7, v255, 17
	s_waitcnt vmcnt(1)
	v_lshlrev_b32_e32 v80, 16, v14
	v_and_b32_e32 v81, 0xffff0000, v14
	v_pk_fma_f32 v[64:65], v[4:5], v[80:81], v[64:65] op_sel_hi:[0,1,1]
	s_waitcnt vmcnt(0)
	v_lshlrev_b32_e32 v80, 16, v6
	v_and_b32_e32 v81, 0xffff0000, v6
	v_pk_mul_f32 v[64:65], v[64:65], v[80:81]
	v_lshlrev_b32_e32 v6, 16, v7
	v_cvt_pk_bf16_f32 v14, v64, v65
	v_pk_mul_f32 v[64:65], v[66:67], v[2:3] op_sel_hi:[1,0]
	v_lshlrev_b32_e32 v66, 16, v15
	v_and_b32_e32 v67, 0xffff0000, v15
	v_pk_fma_f32 v[64:65], v[4:5], v[66:67], v[64:65] op_sel_hi:[0,1,1]
	v_and_b32_e32 v7, 0xffff0000, v7
	v_pk_mul_f32 v[6:7], v[64:65], v[6:7]
	s_nop 0
	v_cvt_pk_bf16_f32 v15, v6, v7
	v_lshl_add_u64 v[6:7], s[4:5], 0, v[12:13]
	v_lshl_add_u64 v[6:7], v[6:7], 0, v[0:1]
	v_or_b32_e32 v12, 16, v0
	v_mov_b32_e32 v13, v1
	global_store_dwordx2 v[6:7], v[14:15], off
	v_lshl_add_u64 v[12:13], v[10:11], 0, v[12:13]
	v_mov_b32_e32 v12, v206
	v_mov_b32_e32 v13, v207
	s_nop 0
	v_mov_b32_e32 v14, v208
	v_mov_b32_e32 v15, v209
	v_lshlrev_b32_e32 v66, 16, v12
	v_lshlrev_b32_e32 v64, 16, v14
	v_and_b32_e32 v65, 0xffff0000, v14
	v_pk_mul_f32 v[64:65], v[4:5], v[64:65] op_sel_hi:[0,1]
	v_pk_fma_f32 v[64:65], v[68:69], v[2:3], v[64:65] op_sel_hi:[1,0,1]
	v_and_b32_e32 v67, 0xffff0000, v12
	v_lshlrev_b32_e32 v14, 16, v15
	v_and_b32_e32 v15, 0xffff0000, v15
	v_pk_mul_f32 v[64:65], v[64:65], v[66:67]
	v_pk_mul_f32 v[14:15], v[4:5], v[14:15] op_sel_hi:[0,1]
	v_cvt_pk_bf16_f32 v12, v64, v65
	v_pk_fma_f32 v[14:15], v[70:71], v[2:3], v[14:15] op_sel_hi:[1,0,1]
	v_lshlrev_b32_e32 v64, 16, v13
	v_and_b32_e32 v65, 0xffff0000, v13
	v_pk_mul_f32 v[14:15], v[14:15], v[64:65]
	s_nop 0
	v_cvt_pk_bf16_f32 v13, v14, v15
	global_store_dwordx2 v[6:7], v[12:13], off offset:16
	v_or_b32_e32 v12, 32, v0
	v_mov_b32_e32 v13, v1
	v_lshl_add_u64 v[12:13], v[10:11], 0, v[12:13]
	v_mov_b32_e32 v12, v210
	v_mov_b32_e32 v13, v211
	s_nop 0
	v_mov_b32_e32 v14, v212
	v_mov_b32_e32 v15, v213
	v_lshlrev_b32_e32 v66, 16, v12
	v_lshlrev_b32_e32 v64, 16, v14
	v_and_b32_e32 v65, 0xffff0000, v14
	v_pk_mul_f32 v[64:65], v[4:5], v[64:65] op_sel_hi:[0,1]
	v_pk_fma_f32 v[64:65], v[72:73], v[2:3], v[64:65] op_sel_hi:[1,0,1]
	v_and_b32_e32 v67, 0xffff0000, v12
	v_lshlrev_b32_e32 v14, 16, v15
; DI unsigned pack2(float a, float b) { v2f f = {a, b}; return __builtin_bit_cast(unsigned, __builtin_convertvector(f, v2bf)); }
; DI float bflo(unsigned v) { return __uint_as_float(v << 16); }
; DI float bfhi(unsigned v) { return __uint_as_float(v & 0xffff0000u); }
; DI void dil_attn_phase(const Params& p, char* smem) {
;     ...
; #pragma unroll
;     for (int dc = 0; dc < 4; ++dc)
; #pragma unroll
;       for (int g4 = 0; g4 < 4; ++g4) {
;         const int col = hg * 256 + half * 128 + 32 * dc + 8 * g4 + 4 * h;
;         const u32x2 zz = *(const u32x2*)(p.qkvz + tok * LD + 2560 + col);
;         const u32x2 pp = *(const u32x2*)(p.part + tok * 1024 + col);
;         u32x2 o;
;         o.x = pack2((ot[dc][4 * g4] * cj + bflo(pp.x) * c1) * bflo(zz.x), (ot[dc][4 * g4 + 1] * cj + bfhi(pp.x) * c1) * bfhi(zz.x));
;         o.y = pack2((ot[dc][4 * g4 + 2] * cj + bflo(pp.y) * c1) * bflo(zz.y), (ot[dc][4 * g4 + 3] * cj + bfhi(pp.y) * c1) * bfhi(zz.y));
;         *(u32x2*)(p.u + tok * 1024 + col) = o;
	v_and_b32_e32 v15, 0xffff0000, v15
	v_pk_mul_f32 v[64:65], v[64:65], v[66:67]
	v_pk_mul_f32 v[14:15], v[4:5], v[14:15] op_sel_hi:[0,1]
	v_cvt_pk_bf16_f32 v12, v64, v65
	v_pk_fma_f32 v[14:15], v[74:75], v[2:3], v[14:15] op_sel_hi:[1,0,1]
	v_lshlrev_b32_e32 v64, 16, v13
	v_and_b32_e32 v65, 0xffff0000, v13
	v_pk_mul_f32 v[14:15], v[14:15], v[64:65]
	s_nop 0
	v_cvt_pk_bf16_f32 v13, v14, v15
	global_store_dwordx2 v[6:7], v[12:13], off offset:32
	v_or_b32_e32 v12, 48, v0
	v_mov_b32_e32 v13, v1
	v_lshl_add_u64 v[12:13], v[10:11], 0, v[12:13]
	v_mov_b32_e32 v12, v214
	v_mov_b32_e32 v13, v215
	s_nop 0
	v_mov_b32_e32 v14, v216
	v_mov_b32_e32 v15, v217
	v_lshlrev_b32_e32 v66, 16, v12
	v_lshlrev_b32_e32 v64, 16, v14
	v_and_b32_e32 v65, 0xffff0000, v14
	v_pk_mul_f32 v[64:65], v[4:5], v[64:65] op_sel_hi:[0,1]
	v_pk_fma_f32 v[64:65], v[76:77], v[2:3], v[64:65] op_sel_hi:[1,0,1]
	v_and_b32_e32 v67, 0xffff0000, v12
	v_lshlrev_b32_e32 v14, 16, v15
	v_and_b32_e32 v15, 0xffff0000, v15
	v_pk_mul_f32 v[64:65], v[64:65], v[66:67]
	v_pk_mul_f32 v[14:15], v[4:5], v[14:15] op_sel_hi:[0,1]
	v_cvt_pk_bf16_f32 v12, v64, v65
	v_pk_fma_f32 v[14:15], v[78:79], v[2:3], v[14:15] op_sel_hi:[1,0,1]
	v_lshlrev_b32_e32 v64, 16, v13
	v_and_b32_e32 v65, 0xffff0000, v13
	v_pk_mul_f32 v[14:15], v[14:15], v[64:65]
	s_nop 0
	v_cvt_pk_bf16_f32 v13, v14, v15
	global_store_dwordx2 v[6:7], v[12:13], off offset:48
	v_or_b32_e32 v12, 64, v0
	v_mov_b32_e32 v13, v1
	v_lshl_add_u64 v[12:13], v[10:11], 0, v[12:13]
	v_mov_b32_e32 v12, v218
	v_mov_b32_e32 v13, v219
	s_nop 0
	v_mov_b32_e32 v14, v220
	v_mov_b32_e32 v15, v221
	v_lshlrev_b32_e32 v64, 16, v14
	v_and_b32_e32 v65, 0xffff0000, v14
	v_pk_mul_f32 v[64:65], v[4:5], v[64:65] op_sel_hi:[0,1]
	v_pk_fma_f32 v[48:49], v[48:49], v[2:3], v[64:65] op_sel_hi:[1,0,1]
	v_lshlrev_b32_e32 v64, 16, v12
	v_and_b32_e32 v65, 0xffff0000, v12
	v_lshlrev_b32_e32 v14, 16, v15
	v_and_b32_e32 v15, 0xffff0000, v15
	v_pk_mul_f32 v[48:49], v[48:49], v[64:65]
	v_pk_mul_f32 v[14:15], v[4:5], v[14:15] op_sel_hi:[0,1]
	v_cvt_pk_bf16_f32 v12, v48, v49
	v_pk_fma_f32 v[14:15], v[50:51], v[2:3], v[14:15] op_sel_hi:[1,0,1]
	v_lshlrev_b32_e32 v48, 16, v13
	v_and_b32_e32 v49, 0xffff0000, v13
	v_pk_mul_f32 v[14:15], v[14:15], v[48:49]
	s_nop 0
	v_cvt_pk_bf16_f32 v13, v14, v15
	global_store_dwordx2 v[6:7], v[12:13], off offset:64
	v_or_b32_e32 v12, 0x50, v0
	v_mov_b32_e32 v13, v1
	v_lshl_add_u64 v[12:13], v[10:11], 0, v[12:13]
	v_mov_b32_e32 v12, v224
	v_mov_b32_e32 v13, v225
	s_nop 0
	v_mov_b32_e32 v14, v226
	v_mov_b32_e32 v15, v227
	v_lshlrev_b32_e32 v50, 16, v12
	v_lshlrev_b32_e32 v48, 16, v14
	v_and_b32_e32 v49, 0xffff0000, v14
	v_pk_mul_f32 v[48:49], v[4:5], v[48:49] op_sel_hi:[0,1]
	v_pk_fma_f32 v[48:49], v[52:53], v[2:3], v[48:49] op_sel_hi:[1,0,1]
	v_and_b32_e32 v51, 0xffff0000, v12
	v_lshlrev_b32_e32 v14, 16, v15
	v_and_b32_e32 v15, 0xffff0000, v15
	v_pk_mul_f32 v[48:49], v[48:49], v[50:51]
	v_pk_mul_f32 v[14:15], v[4:5], v[14:15] op_sel_hi:[0,1]
	v_cvt_pk_bf16_f32 v12, v48, v49
	v_pk_fma_f32 v[14:15], v[54:55], v[2:3], v[14:15] op_sel_hi:[1,0,1]
	v_lshlrev_b32_e32 v48, 16, v13
	v_and_b32_e32 v49, 0xffff0000, v13
	v_pk_mul_f32 v[14:15], v[14:15], v[48:49]
	s_nop 0
	v_cvt_pk_bf16_f32 v13, v14, v15
	global_store_dwordx2 v[6:7], v[12:13], off offset:80
	v_or_b32_e32 v12, 0x60, v0
	v_mov_b32_e32 v13, v1
	v_lshl_add_u64 v[12:13], v[10:11], 0, v[12:13]
	v_mov_b32_e32 v12, v228
	v_mov_b32_e32 v13, v229
	s_nop 0
	v_mov_b32_e32 v14, v230
	v_mov_b32_e32 v15, v231
	v_lshlrev_b32_e32 v50, 16, v12
	v_lshlrev_b32_e32 v48, 16, v14
	v_and_b32_e32 v49, 0xffff0000, v14
	v_pk_mul_f32 v[48:49], v[4:5], v[48:49] op_sel_hi:[0,1]
	v_pk_fma_f32 v[48:49], v[56:57], v[2:3], v[48:49] op_sel_hi:[1,0,1]
	v_and_b32_e32 v51, 0xffff0000, v12
	v_lshlrev_b32_e32 v14, 16, v15
	v_and_b32_e32 v15, 0xffff0000, v15
	v_pk_mul_f32 v[48:49], v[48:49], v[50:51]
	v_pk_mul_f32 v[14:15], v[4:5], v[14:15] op_sel_hi:[0,1]
	v_cvt_pk_bf16_f32 v12, v48, v49
	v_pk_fma_f32 v[14:15], v[58:59], v[2:3], v[14:15] op_sel_hi:[1,0,1]
	v_lshlrev_b32_e32 v48, 16, v13
	v_and_b32_e32 v49, 0xffff0000, v13
	v_pk_mul_f32 v[14:15], v[14:15], v[48:49]
	s_nop 0
	v_cvt_pk_bf16_f32 v13, v14, v15
	global_store_dwordx2 v[6:7], v[12:13], off offset:96
	v_or_b32_e32 v12, 0x70, v0
	v_mov_b32_e32 v13, v1
	v_lshl_add_u64 v[12:13], v[10:11], 0, v[12:13]
	v_mov_b32_e32 v12, v232
	v_mov_b32_e32 v13, v233
	s_nop 0
	v_mov_b32_e32 v14, v234
	v_mov_b32_e32 v15, v235
	v_lshlrev_b32_e32 v50, 16, v12
	v_lshlrev_b32_e32 v48, 16, v14
	v_and_b32_e32 v49, 0xffff0000, v14
	v_pk_mul_f32 v[48:49], v[4:5], v[48:49] op_sel_hi:[0,1]
	v_pk_fma_f32 v[48:49], v[60:61], v[2:3], v[48:49] op_sel_hi:[1,0,1]
	v_and_b32_e32 v51, 0xffff0000, v12
	v_lshlrev_b32_e32 v14, 16, v15
	v_and_b32_e32 v15, 0xffff0000, v15
	v_pk_mul_f32 v[48:49], v[48:49], v[50:51]
	v_pk_mul_f32 v[14:15], v[4:5], v[14:15] op_sel_hi:[0,1]
	v_cvt_pk_bf16_f32 v12, v48, v49
	v_pk_fma_f32 v[14:15], v[62:63], v[2:3], v[14:15] op_sel_hi:[1,0,1]
	v_lshlrev_b32_e32 v48, 16, v13
	v_and_b32_e32 v49, 0xffff0000, v13
	v_pk_mul_f32 v[14:15], v[14:15], v[48:49]
	s_nop 0
	v_cvt_pk_bf16_f32 v13, v14, v15
	global_store_dwordx2 v[6:7], v[12:13], off offset:112
	v_or_b32_e32 v12, 0x80, v0
	v_mov_b32_e32 v13, v1
	v_lshl_add_u64 v[12:13], v[10:11], 0, v[12:13]
	v_mov_b32_e32 v12, v236
	v_mov_b32_e32 v13, v237
	s_nop 0
	v_mov_b32_e32 v14, v238
	v_mov_b32_e32 v15, v239
	v_lshlrev_b32_e32 v48, 16, v14
	v_and_b32_e32 v49, 0xffff0000, v14
	v_pk_mul_f32 v[48:49], v[4:5], v[48:49] op_sel_hi:[0,1]
	v_pk_fma_f32 v[32:33], v[32:33], v[2:3], v[48:49] op_sel_hi:[1,0,1]
	v_lshlrev_b32_e32 v48, 16, v12
	v_and_b32_e32 v49, 0xffff0000, v12
; DI unsigned pack2(float a, float b) { v2f f = {a, b}; return __builtin_bit_cast(unsigned, __builtin_convertvector(f, v2bf)); }
; DI float bflo(unsigned v) { return __uint_as_float(v << 16); }
; DI float bfhi(unsigned v) { return __uint_as_float(v & 0xffff0000u); }
; DI void dil_attn_phase(const Params& p, char* smem) {
;     ...
; #pragma unroll
;     for (int dc = 0; dc < 4; ++dc)
; #pragma unroll
;       for (int g4 = 0; g4 < 4; ++g4) {
;         const int col = hg * 256 + half * 128 + 32 * dc + 8 * g4 + 4 * h;
;         const u32x2 zz = *(const u32x2*)(p.qkvz + tok * LD + 2560 + col);
;         const u32x2 pp = *(const u32x2*)(p.part + tok * 1024 + col);
;         u32x2 o;
;         o.x = pack2((ot[dc][4 * g4] * cj + bflo(pp.x) * c1) * bflo(zz.x), (ot[dc][4 * g4 + 1] * cj + bfhi(pp.x) * c1) * bfhi(zz.x));
;         o.y = pack2((ot[dc][4 * g4 + 2] * cj + bflo(pp.y) * c1) * bflo(zz.y), (ot[dc][4 * g4 + 3] * cj + bfhi(pp.y) * c1) * bfhi(zz.y));
;         *(u32x2*)(p.u + tok * 1024 + col) = o;
	v_lshlrev_b32_e32 v14, 16, v15
	v_and_b32_e32 v15, 0xffff0000, v15
	v_pk_mul_f32 v[32:33], v[32:33], v[48:49]
	v_pk_mul_f32 v[14:15], v[4:5], v[14:15] op_sel_hi:[0,1]
	v_cvt_pk_bf16_f32 v12, v32, v33
	v_pk_fma_f32 v[14:15], v[34:35], v[2:3], v[14:15] op_sel_hi:[1,0,1]
	v_lshlrev_b32_e32 v32, 16, v13
	v_and_b32_e32 v33, 0xffff0000, v13
	v_pk_mul_f32 v[14:15], v[14:15], v[32:33]
	s_nop 0
	v_cvt_pk_bf16_f32 v13, v14, v15
	global_store_dwordx2 v[6:7], v[12:13], off offset:128
	v_or_b32_e32 v12, 0x90, v0
	v_mov_b32_e32 v13, v1
	v_lshl_add_u64 v[12:13], v[10:11], 0, v[12:13]
	v_mov_b32_e32 v12, v240
	v_mov_b32_e32 v13, v241
	s_nop 0
	v_mov_b32_e32 v14, v242
	v_mov_b32_e32 v15, v243
	v_lshlrev_b32_e32 v34, 16, v12
	v_lshlrev_b32_e32 v32, 16, v14
	v_and_b32_e32 v33, 0xffff0000, v14
	v_pk_mul_f32 v[32:33], v[4:5], v[32:33] op_sel_hi:[0,1]
	v_pk_fma_f32 v[32:33], v[36:37], v[2:3], v[32:33] op_sel_hi:[1,0,1]
	v_and_b32_e32 v35, 0xffff0000, v12
	v_lshlrev_b32_e32 v14, 16, v15
	v_and_b32_e32 v15, 0xffff0000, v15
	v_pk_mul_f32 v[32:33], v[32:33], v[34:35]
	v_pk_mul_f32 v[14:15], v[4:5], v[14:15] op_sel_hi:[0,1]
	v_cvt_pk_bf16_f32 v12, v32, v33
	v_pk_fma_f32 v[14:15], v[38:39], v[2:3], v[14:15] op_sel_hi:[1,0,1]
	v_lshlrev_b32_e32 v32, 16, v13
	v_and_b32_e32 v33, 0xffff0000, v13
	v_pk_mul_f32 v[14:15], v[14:15], v[32:33]
	s_nop 0
	v_cvt_pk_bf16_f32 v13, v14, v15
	global_store_dwordx2 v[6:7], v[12:13], off offset:144
	v_or_b32_e32 v12, 0xa0, v0
	v_mov_b32_e32 v13, v1
	v_lshl_add_u64 v[12:13], v[10:11], 0, v[12:13]
	v_mov_b32_e32 v12, v244
	v_mov_b32_e32 v13, v245
	s_nop 0
	v_mov_b32_e32 v14, v246
	v_mov_b32_e32 v15, v247
	v_lshlrev_b32_e32 v34, 16, v12
	v_lshlrev_b32_e32 v32, 16, v14
	v_and_b32_e32 v33, 0xffff0000, v14
	v_pk_mul_f32 v[32:33], v[4:5], v[32:33] op_sel_hi:[0,1]
	v_pk_fma_f32 v[32:33], v[40:41], v[2:3], v[32:33] op_sel_hi:[1,0,1]
	v_and_b32_e32 v35, 0xffff0000, v12
	v_lshlrev_b32_e32 v14, 16, v15
	v_and_b32_e32 v15, 0xffff0000, v15
	v_pk_mul_f32 v[32:33], v[32:33], v[34:35]
	v_pk_mul_f32 v[14:15], v[4:5], v[14:15] op_sel_hi:[0,1]
	v_cvt_pk_bf16_f32 v12, v32, v33
	v_pk_fma_f32 v[14:15], v[42:43], v[2:3], v[14:15] op_sel_hi:[1,0,1]
	v_lshlrev_b32_e32 v32, 16, v13
	v_and_b32_e32 v33, 0xffff0000, v13
	v_pk_mul_f32 v[14:15], v[14:15], v[32:33]
	s_nop 0
	v_cvt_pk_bf16_f32 v13, v14, v15
	global_store_dwordx2 v[6:7], v[12:13], off offset:160
	v_or_b32_e32 v12, 0xb0, v0
	v_mov_b32_e32 v13, v1
	v_lshl_add_u64 v[12:13], v[10:11], 0, v[12:13]
	v_mov_b32_e32 v12, v248
	v_mov_b32_e32 v13, v249
	s_nop 0
	v_mov_b32_e32 v14, v250
	v_mov_b32_e32 v15, v251
	v_lshlrev_b32_e32 v34, 16, v12
	v_lshlrev_b32_e32 v32, 16, v14
	v_and_b32_e32 v33, 0xffff0000, v14
	v_pk_mul_f32 v[32:33], v[4:5], v[32:33] op_sel_hi:[0,1]
	v_pk_fma_f32 v[32:33], v[44:45], v[2:3], v[32:33] op_sel_hi:[1,0,1]
	v_and_b32_e32 v35, 0xffff0000, v12
	v_lshlrev_b32_e32 v14, 16, v15
	v_and_b32_e32 v15, 0xffff0000, v15
	v_pk_mul_f32 v[32:33], v[32:33], v[34:35]
	v_pk_mul_f32 v[14:15], v[4:5], v[14:15] op_sel_hi:[0,1]
	v_cvt_pk_bf16_f32 v12, v32, v33
	v_pk_fma_f32 v[14:15], v[46:47], v[2:3], v[14:15] op_sel_hi:[1,0,1]
	v_lshlrev_b32_e32 v32, 16, v13
	v_and_b32_e32 v33, 0xffff0000, v13
	v_pk_mul_f32 v[14:15], v[14:15], v[32:33]
	s_nop 0
	v_cvt_pk_bf16_f32 v13, v14, v15
	global_store_dwordx2 v[6:7], v[12:13], off offset:176
	v_or_b32_e32 v12, 0xc0, v0
	v_mov_b32_e32 v13, v1
	v_lshl_add_u64 v[12:13], v[10:11], 0, v[12:13]
	global_load_dwordx2 v[12:13], v[12:13], off
	s_nop 0
	global_load_dwordx2 v[14:15], v[8:9], off offset:192
	s_waitcnt vmcnt(0)
; DI unsigned pack2(float a, float b) { v2f f = {a, b}; return __builtin_bit_cast(unsigned, __builtin_convertvector(f, v2bf)); }
; DI float bflo(unsigned v) { return __uint_as_float(v << 16); }
; DI float bfhi(unsigned v) { return __uint_as_float(v & 0xffff0000u); }
; DI void dil_attn_phase(const Params& p, char* smem) {
;     ...
; #pragma unroll
;     for (int dc = 0; dc < 4; ++dc)
; #pragma unroll
;       for (int g4 = 0; g4 < 4; ++g4) {
;         const int col = hg * 256 + half * 128 + 32 * dc + 8 * g4 + 4 * h;
;         const u32x2 zz = *(const u32x2*)(p.qkvz + tok * LD + 2560 + col);
;         const u32x2 pp = *(const u32x2*)(p.part + tok * 1024 + col);
;         u32x2 o;
;         o.x = pack2((ot[dc][4 * g4] * cj + bflo(pp.x) * c1) * bflo(zz.x), (ot[dc][4 * g4 + 1] * cj + bfhi(pp.x) * c1) * bfhi(zz.x));
;         o.y = pack2((ot[dc][4 * g4 + 2] * cj + bflo(pp.y) * c1) * bflo(zz.y), (ot[dc][4 * g4 + 3] * cj + bfhi(pp.y) * c1) * bfhi(zz.y));
;         *(u32x2*)(p.u + tok * 1024 + col) = o;
	v_lshlrev_b32_e32 v32, 16, v14
	v_and_b32_e32 v33, 0xffff0000, v14
	v_pk_mul_f32 v[32:33], v[4:5], v[32:33] op_sel_hi:[0,1]
	v_pk_fma_f32 v[16:17], v[16:17], v[2:3], v[32:33] op_sel_hi:[1,0,1]
	v_lshlrev_b32_e32 v32, 16, v12
	v_and_b32_e32 v33, 0xffff0000, v12
	v_lshlrev_b32_e32 v14, 16, v15
	v_and_b32_e32 v15, 0xffff0000, v15
	v_pk_mul_f32 v[16:17], v[16:17], v[32:33]
	v_pk_mul_f32 v[14:15], v[4:5], v[14:15] op_sel_hi:[0,1]
	v_cvt_pk_bf16_f32 v12, v16, v17
	v_pk_fma_f32 v[14:15], v[18:19], v[2:3], v[14:15] op_sel_hi:[1,0,1]
	v_lshlrev_b32_e32 v16, 16, v13
	v_and_b32_e32 v17, 0xffff0000, v13
	v_pk_mul_f32 v[14:15], v[14:15], v[16:17]
	s_nop 0
	v_cvt_pk_bf16_f32 v13, v14, v15
	global_store_dwordx2 v[6:7], v[12:13], off offset:192
	v_or_b32_e32 v12, 0xd0, v0
	v_mov_b32_e32 v13, v1
	v_lshl_add_u64 v[12:13], v[10:11], 0, v[12:13]
	global_load_dwordx2 v[12:13], v[12:13], off
	s_nop 0
	global_load_dwordx2 v[14:15], v[8:9], off offset:208
	s_waitcnt vmcnt(1)
	v_lshlrev_b32_e32 v18, 16, v12
	s_waitcnt vmcnt(0)
	v_lshlrev_b32_e32 v16, 16, v14
	v_and_b32_e32 v17, 0xffff0000, v14
	v_pk_mul_f32 v[16:17], v[4:5], v[16:17] op_sel_hi:[0,1]
	v_pk_fma_f32 v[16:17], v[20:21], v[2:3], v[16:17] op_sel_hi:[1,0,1]
	v_and_b32_e32 v19, 0xffff0000, v12
	v_lshlrev_b32_e32 v14, 16, v15
	v_and_b32_e32 v15, 0xffff0000, v15
	v_pk_mul_f32 v[16:17], v[16:17], v[18:19]
	v_pk_mul_f32 v[14:15], v[4:5], v[14:15] op_sel_hi:[0,1]
	v_cvt_pk_bf16_f32 v12, v16, v17
	v_pk_fma_f32 v[14:15], v[22:23], v[2:3], v[14:15] op_sel_hi:[1,0,1]
	v_lshlrev_b32_e32 v16, 16, v13
	v_and_b32_e32 v17, 0xffff0000, v13
	v_pk_mul_f32 v[14:15], v[14:15], v[16:17]
	s_nop 0
	v_cvt_pk_bf16_f32 v13, v14, v15
	global_store_dwordx2 v[6:7], v[12:13], off offset:208
	v_or_b32_e32 v12, 0xe0, v0
	v_mov_b32_e32 v13, v1
	v_lshl_add_u64 v[12:13], v[10:11], 0, v[12:13]
	global_load_dwordx2 v[12:13], v[12:13], off
	s_nop 0
	global_load_dwordx2 v[14:15], v[8:9], off offset:224
	v_or_b32_e32 v0, 0xf0, v0
	v_lshl_add_u64 v[10:11], v[10:11], 0, v[0:1]
	s_waitcnt vmcnt(1)
	v_lshlrev_b32_e32 v18, 16, v12
	s_waitcnt vmcnt(0)
	v_lshlrev_b32_e32 v16, 16, v14
	v_and_b32_e32 v17, 0xffff0000, v14
	v_pk_mul_f32 v[16:17], v[4:5], v[16:17] op_sel_hi:[0,1]
	v_pk_fma_f32 v[16:17], v[24:25], v[2:3], v[16:17] op_sel_hi:[1,0,1]
	v_and_b32_e32 v19, 0xffff0000, v12
	v_lshlrev_b32_e32 v14, 16, v15
	v_and_b32_e32 v15, 0xffff0000, v15
	v_pk_mul_f32 v[16:17], v[16:17], v[18:19]
	v_pk_mul_f32 v[14:15], v[4:5], v[14:15] op_sel_hi:[0,1]
	v_cvt_pk_bf16_f32 v12, v16, v17
	v_pk_fma_f32 v[14:15], v[26:27], v[2:3], v[14:15] op_sel_hi:[1,0,1]
	v_lshlrev_b32_e32 v16, 16, v13
	v_and_b32_e32 v17, 0xffff0000, v13
	v_pk_mul_f32 v[14:15], v[14:15], v[16:17]
	s_nop 0
	v_cvt_pk_bf16_f32 v13, v14, v15
	global_store_dwordx2 v[6:7], v[12:13], off offset:224
	global_load_dwordx2 v[10:11], v[10:11], off
	s_nop 0
	global_load_dwordx2 v[8:9], v[8:9], off offset:240
	s_waitcnt vmcnt(1)
	v_lshlrev_b32_e32 v14, 16, v10
	s_waitcnt vmcnt(0)
	v_lshlrev_b32_e32 v12, 16, v8
	v_and_b32_e32 v13, 0xffff0000, v8
	v_pk_mul_f32 v[12:13], v[4:5], v[12:13] op_sel_hi:[0,1]
	v_pk_fma_f32 v[12:13], v[28:29], v[2:3], v[12:13] op_sel_hi:[1,0,1]
	v_and_b32_e32 v15, 0xffff0000, v10
	v_pk_mul_f32 v[12:13], v[12:13], v[14:15]
	s_nop 0
	v_cvt_pk_bf16_f32 v8, v12, v13
	v_lshlrev_b32_e32 v12, 16, v9
	v_and_b32_e32 v13, 0xffff0000, v9
	v_pk_mul_f32 v[4:5], v[4:5], v[12:13] op_sel_hi:[0,1]
	v_pk_fma_f32 v[2:3], v[30:31], v[2:3], v[4:5] op_sel_hi:[1,0,1]
	v_lshlrev_b32_e32 v4, 16, v11
	v_and_b32_e32 v5, 0xffff0000, v11
	v_pk_mul_f32 v[2:3], v[2:3], v[4:5]
	s_nop 0
	v_cvt_pk_bf16_f32 v9, v2, v3
	global_store_dwordx2 v[6:7], v[8:9], off offset:240

; #define MFMA(a, b, c) __builtin_amdgcn_mfma_f32_32x32x16_bf16((a), (b), (c), 0, 0, 0)
; DI void qk_acc(f32x16 (&st)[2], const bf16x8 (&qf)[4], const char* sb, const int (&foff)[4]) {
; #pragma unroll
;   for (int kb = 0; kb < 2; ++kb)
; #pragma unroll
;     for (int ks = 0; ks < 4; ++ks) {
;       const bf16x8 kf = *(const bf16x8*)(sb + kb * 4096 + foff[ks]);
;       st[kb] = MFMA(kf, qf[ks], st[kb]);
;     }
; }
; template <int DV, bool SEL, bool TERM> ...
;     ...
;     const float dbase = (float)(tqp - kp_mul * (k0 + 4 * h));
;     f32x16 st[2];
;     if (relevant) {
;       const float tb = -slope2 * dbase - mref;
; #pragma unroll
;       for (int kb = 0; kb < 2; ++kb)
; #pragma unroll
;         for (int i = 0; i < 16; ++i) st[kb][i] = __builtin_fmaf(sk, (float)(kb * 32 + (i & 3) + 8 * (i >> 2)), tb);
;       qk_acc(st, qf, sb, foff);
.LBB0_2092:
	s_lshl_b32 s1, s8, 6
	v_or_b32_e32 v0, s1, v174
	v_sub_u32_e32 v2, v159, v0
	s_or_b32 s4, s1, 63
	v_cvt_f32_i32_e32 v0, v2
	s_mul_hi_u32 s0, s96, 0xaaaaaaab
	s_waitcnt lgkmcnt(0)
	v_subrev_u32_e32 v3, s1, v161
	v_subrev_u32_e32 v4, s4, v160
	s_lshr_b32 s0, s0, 1
	v_cmp_lt_i32_e32 vcc, -1, v3
	v_cmp_gt_i32_e64 s[4:5], s97, v4
	s_mul_i32 s0, s0, 0xfffee000
	s_and_b64 s[4:5], vcc, s[4:5]
	s_barrier
	s_and_saveexec_b64 s[8:9], s[4:5]
	s_cbranch_execz .LBB0_2094
	s_add_i32 s1, s19, s0
	v_add_u32_e32 v5, s1, v181
	ds_read_b128 v[6:9], v5
	v_fma_f32 v10, -v136, v0, -v156
	v_fma_f32 v80, 0, v136, v10
	v_add_f32_e32 v81, v136, v10
	v_pk_fma_f32 v[82:83], v[144:145], s[24:25], v[10:11] op_sel_hi:[1,1,0]
	v_pk_fma_f32 v[84:85], v[144:145], s[26:27], v[10:11] op_sel_hi:[1,1,0]
	v_pk_fma_f32 v[86:87], v[144:145], s[28:29], v[10:11] op_sel_hi:[1,1,0]
	v_pk_fma_f32 v[88:89], v[144:145], s[30:31], v[10:11] op_sel_hi:[1,1,0]
	v_pk_fma_f32 v[90:91], v[144:145], s[34:35], v[10:11] op_sel_hi:[1,1,0]
	v_pk_fma_f32 v[92:93], v[144:145], s[36:37], v[10:11] op_sel_hi:[1,1,0]
	v_pk_fma_f32 v[94:95], v[144:145], s[38:39], v[10:11] op_sel_hi:[1,1,0]
	v_add_u32_e32 v11, s1, v183
	v_add_u32_e32 v12, s1, v184
	v_add_u32_e32 v13, s1, v182
	ds_read_b128 v[224:227], v11
	ds_read_b128 v[228:231], v12
	ds_read_b128 v[232:235], v13
	ds_read_b128 v[236:239], v5 offset:4096
	ds_read_b128 v[240:243], v11 offset:4096
	ds_read_b128 v[244:247], v12 offset:4096
	ds_read_b128 v[248:251], v13 offset:4096
	s_waitcnt lgkmcnt(7)
	v_mfma_f32_32x32x16_bf16 v[80:95], v[6:9], v[112:115], v[80:95]
	v_mov_b32_e32 v137, v136
	v_fma_f32 v110, v136, s40, v10
	v_fma_f32 v111, v137, s41, v10
	v_pk_fma_f32 v[108:109], v[136:137], s[42:43], v[10:11] op_sel_hi:[1,1,0]
	v_pk_fma_f32 v[106:107], v[136:137], s[44:45], v[10:11] op_sel_hi:[1,1,0]
	v_pk_fma_f32 v[104:105], v[136:137], s[46:47], v[10:11] op_sel_hi:[1,1,0]
	s_waitcnt lgkmcnt(6)
	v_mfma_f32_32x32x16_bf16 v[80:95], v[224:227], v[116:119], v[80:95]
	v_fma_f32 v102, v136, s48, v10
	v_fma_f32 v103, v137, s49, v10
	v_fma_f32 v100, v136, s50, v10
	v_fma_f32 v101, v137, s51, v10
	v_pk_fma_f32 v[98:99], v[136:137], s[52:53], v[10:11] op_sel_hi:[1,1,0]
	v_pk_fma_f32 v[96:97], v[146:147], s[54:55], v[10:11] op_sel_hi:[1,1,0]
	s_waitcnt lgkmcnt(5)
	v_mfma_f32_32x32x16_bf16 v[80:95], v[228:231], v[120:123], v[80:95]
	s_waitcnt lgkmcnt(4)
	v_mfma_f32_32x32x16_bf16 v[80:95], v[232:235], v[124:127], v[80:95]
	s_waitcnt lgkmcnt(3)
	v_mfma_f32_32x32x16_bf16 v[96:111], v[236:239], v[112:115], v[96:111]
	s_waitcnt lgkmcnt(2)
	v_mfma_f32_32x32x16_bf16 v[96:111], v[240:243], v[116:119], v[96:111]
	s_waitcnt lgkmcnt(1)
	v_mfma_f32_32x32x16_bf16 v[96:111], v[244:247], v[120:123], v[96:111]
	s_waitcnt lgkmcnt(0)
	v_mfma_f32_32x32x16_bf16 v[96:111], v[248:251], v[124:127], v[96:111]

; #define MFMA(a, b, c) __builtin_amdgcn_mfma_f32_32x32x16_bf16((a), (b), (c), 0, 0, 0)
; DI void qk_acc(f32x16 (&st)[2], const bf16x8 (&qf)[4], const char* sb, const int (&foff)[4]) {
; #pragma unroll
;   for (int kb = 0; kb < 2; ++kb)
; #pragma unroll
;     for (int ks = 0; ks < 4; ++ks) {
;       const bf16x8 kf = *(const bf16x8*)(sb + kb * 4096 + foff[ks]);
;       st[kb] = MFMA(kf, qf[ks], st[kb]);
;     }
; }
; template <int DV, bool SEL, bool TERM> ...
;     ...
;     const float dbase = (float)(tqp - kp_mul * (k0 + 4 * h));
;     f32x16 st[2];
;     if (relevant) {
;       const float tb = -slope2 * dbase - mref;
; #pragma unroll
;       for (int kb = 0; kb < 2; ++kb)
; #pragma unroll
;         for (int i = 0; i < 16; ++i) st[kb][i] = __builtin_fmaf(sk, (float)(kb * 32 + (i & 3) + 8 * (i >> 2)), tb);
;       qk_acc(st, qf, sb, foff);
.LBB0_2116:
	s_lshl_b32 s1, s8, 6
	v_or_b32_e32 v0, s1, v158
	v_sub_u32_e32 v116, v134, v0
	s_or_b32 s4, s1, 63
	v_cvt_f32_i32_e32 v0, v116
	s_mul_hi_u32 s0, s19, 0xaaaaaaab
	s_waitcnt lgkmcnt(0)
	v_subrev_u32_e32 v117, s1, v136
	v_subrev_u32_e32 v118, s4, v135
	s_lshr_b32 s0, s0, 1
	v_cmp_lt_i32_e32 vcc, -1, v117
	v_cmp_gt_i32_e64 s[4:5], s97, v118
	s_mul_i32 s0, s0, 0xfffee000
	s_and_b64 s[4:5], vcc, s[4:5]
	s_barrier
	s_and_saveexec_b64 s[8:9], s[4:5]
	s_cbranch_execz .LBB0_2118
	s_add_i32 s1, s17, s0
	v_add_u32_e32 v119, s1, v165
	ds_read_b128 v[96:99], v119
	v_fma_f32 v170, -v14, v0, -v156
	v_fma_f32 v80, 0, v14, v170
	v_add_f32_e32 v81, v14, v170
	v_pk_fma_f32 v[82:83], v[126:127], s[24:25], v[170:171] op_sel_hi:[1,1,0]
	v_pk_fma_f32 v[84:85], v[126:127], s[26:27], v[170:171] op_sel_hi:[1,1,0]
	v_pk_fma_f32 v[86:87], v[126:127], s[28:29], v[170:171] op_sel_hi:[1,1,0]
	v_pk_fma_f32 v[88:89], v[126:127], s[30:31], v[170:171] op_sel_hi:[1,1,0]
	v_pk_fma_f32 v[90:91], v[126:127], s[34:35], v[170:171] op_sel_hi:[1,1,0]
	v_pk_fma_f32 v[92:93], v[126:127], s[36:37], v[170:171] op_sel_hi:[1,1,0]
	v_pk_fma_f32 v[94:95], v[126:127], s[38:39], v[170:171] op_sel_hi:[1,1,0]
	v_add_u32_e32 v169, s1, v167
	v_add_u32_e32 v174, s1, v168
	v_add_u32_e32 v175, s1, v166
	ds_read_b128 v[224:227], v169
	ds_read_b128 v[228:231], v174
	ds_read_b128 v[232:235], v175
	ds_read_b128 v[236:239], v119 offset:4096
	ds_read_b128 v[240:243], v169 offset:4096
	ds_read_b128 v[244:247], v174 offset:4096
	ds_read_b128 v[248:251], v175 offset:4096
	s_waitcnt lgkmcnt(7)
	v_mfma_f32_32x32x16_bf16 v[80:95], v[96:99], v[2:5], v[80:95]
	v_mov_b32_e32 v15, v14
	v_fma_f32 v110, v14, s40, v170
	v_fma_f32 v111, v15, s41, v170
	v_pk_fma_f32 v[108:109], v[14:15], s[42:43], v[170:171] op_sel_hi:[1,1,0]
	v_pk_fma_f32 v[106:107], v[14:15], s[44:45], v[170:171] op_sel_hi:[1,1,0]
	v_pk_fma_f32 v[104:105], v[14:15], s[46:47], v[170:171] op_sel_hi:[1,1,0]
	s_waitcnt lgkmcnt(6)
	v_mfma_f32_32x32x16_bf16 v[80:95], v[224:227], v[6:9], v[80:95]
	v_fma_f32 v102, v14, s48, v170
	v_fma_f32 v103, v15, s49, v170
	v_fma_f32 v100, v14, s50, v170
	v_fma_f32 v101, v15, s51, v170
	s_waitcnt lgkmcnt(5)
	v_mfma_f32_32x32x16_bf16 v[80:95], v[228:231], v[10:13], v[80:95]
	s_waitcnt lgkmcnt(4)
	v_mfma_f32_32x32x16_bf16 v[80:95], v[232:235], v[112:115], v[80:95]
	v_fma_f32 v98, v14, s52, v170
	v_fma_f32 v99, v15, s53, v170
	v_fma_f32 v96, v132, s54, v170
	v_fma_f32 v97, v133, s55, v170
	s_waitcnt lgkmcnt(3)
	s_nop 0
	v_mfma_f32_32x32x16_bf16 v[96:111], v[236:239], v[2:5], v[96:111]
	s_waitcnt lgkmcnt(2)
	v_mfma_f32_32x32x16_bf16 v[96:111], v[240:243], v[6:9], v[96:111]
	s_waitcnt lgkmcnt(1)
	v_mfma_f32_32x32x16_bf16 v[96:111], v[244:247], v[10:13], v[96:111]
	s_waitcnt lgkmcnt(0)
	v_mfma_f32_32x32x16_bf16 v[96:111], v[248:251], v[112:115], v[96:111]
